# stacked cache hints: combine-phase non-temporal loads plus non-temporal stores for the GLU-epilogue residual rows and the S5 scan outputs
# speedup vs baseline: 1.0011x; 1.0011x over previous
; DI void s5_phase(const KArgs& a, int zz, int o, const bf16_t* H, bf16_t* YF, bf16_t* YB, LAS unsigned char* lds, int G, int bid, int wave, int lane) {
;     ...
;         auto loadu = [&](const int ci) __attribute__((always_inline)) -> u32x4 {
;             const int cc = ci < 272 ? ci : 271;
;             u32x4 r = *(const u32x4*)(Hg + (chunk_row(cc) + fr) * D);
;             const bool keep = fq < 2;
;             r.x = keep ? r.x : 0u; r.y = keep ? r.y : 0u; r.z = keep ? r.z : 0u; r.w = keep ? r.w : 0u;
;             return r; };
;         auto stageA = [&](const u32x4 uu) __attribute__((always_inline)) {
;             const bf16x8 Au = __builtin_bit_cast(bf16x8, uu);
; #pragma unroll
;             for (int nt = 0; nt < 8; ++nt) { const f32x4 acc = MFMA16(Bb[nt], Au, ((f32x4){0.f, 0.f, 0.f, 0.f}));
;                 *(LAS f32x4*)(BU + fr * 132 + 16 * nt + fq * 4) = acc; } };
;         u32x4 u1 = loadu(1), u2 = loadu(2);
;         stageA(loadu(0));
;         S5_CB();
;         size_t rowprev = 0;
;         auto iter = [&](const int ci, const bool do_c) __attribute__((always_inline)) {
;             const size_t row0 = chunk_row(ci);
;             const u32x4 u3 = loadu(ci + 3);
;             f32x2 bu[16];
; #pragma unroll
;             for (int s = 0; s < 16; ++s) { const int tt = DIRC ? 15 - s : s; bu[s] = *(const LAS f32x2*)(BU + tt * 132 + 2 * lane); }
;             bf16x8 Ax[4];
;             if (do_c) {
; #pragma unroll
;                 for (int kb = 0; kb < 4; ++kb) Ax[kb] = *(const LAS bf16x8*)(XS + fr * 68 + kb * 16 + fq * 4); }
;             S5_CB();
;             stageA(u1);
;             S5_CB();
; #pragma unroll
;             for (int s = 0; s < 16; ++s) { const int tt = DIRC ? 15 - s : s;
;                 const float nr = __builtin_fmaf(abr, xr, __builtin_fmaf(nabi, xi, bu[s][0])); const float ni = __builtin_fmaf(abr, xi, __builtin_fmaf(abi, xr, bu[s][1])); xr = nr; xi = ni;
;                 XS[tt * 68 + lane] = pk2(xr, xi); }
;             if (do_c) {
;                 f32x4 ya = (f32x4){0.f, 0.f, 0.f, 0.f};
; #pragma unroll
;                 for (int kb = 0; kb < 4; ++kb) ya = MFMA16(Cb[kb], Ax[kb], ya);
;                 u32x2 w; w.x = pk2(ya[0], ya[1]); w.y = pk2(ya[2], ya[3]); *(u32x2*)(Y + (rowprev + fr) * D + g * 16 + fq * 4) = w; }
;             S5_CB();
;             rowprev = row0; u1 = u2; u2 = u3;
;         };
;         iter(0, false);
.LBB0_414:
	s_waitcnt vmcnt(1)
	v_cndmask_b32_e64 v173, 0, v52, s[38:39]
	v_sub_co_u32_e64 v52, s[26:27], s25, 16
	s_and_b64 s[30:31], s[26:27], exec
	v_readfirstlane_b32 s30, v52
	s_cselect_b32 s30, s25, s30
	s_cselect_b32 s31, 15, 0xff
	s_sub_i32 s30, s31, s30
	s_lshl_b32 s30, s30, 4
	s_ashr_i32 s31, s30, 31
	s_and_b64 s[26:27], s[26:27], exec
	s_cselect_b32 s26, s23, s58
	s_cselect_b32 s27, s24, s59
	s_add_u32 s26, s26, s30
	s_addc_u32 s27, s27, s31
	s_min_i32 s36, s25, 0x10c
	s_cmp_lt_u32 s25, 13
	s_cselect_b64 s[30:31], -1, 0
	s_and_b64 s[34:35], s[30:31], exec
	s_cselect_b32 s34, -3, 13
	s_cselect_b32 s35, 15, 0xff
	s_sub_i32 s34, s34, s36
	s_add_i32 s34, s34, s35
	s_lshl_b32 s34, s34, 4
	s_ashr_i32 s35, s34, 31
	s_and_b64 s[30:31], s[30:31], exec
	s_cselect_b32 s31, s23, s58
	s_cselect_b32 s30, s24, s59
	s_add_u32 s31, s31, s34
	s_addc_u32 s30, s30, s35
	v_cndmask_b32_e64 v172, 0, v53, s[38:39]
	v_mov_b32_e32 v53, s30
	v_or_b32_e32 v52, s31, v104
	v_lshlrev_b64 v[52:53], 11, v[52:53]
	v_lshl_add_u64 v[52:53], v[126:127], 0, v[52:53]
	v_add_u32_e32 v148, v134, v107
	v_cndmask_b32_e64 v170, 0, v55, s[38:39]
	v_cndmask_b32_e64 v171, 0, v54, s[38:39]
	global_load_dwordx4 v[52:55], v[52:53], off
	ds_read_b128 v[56:59], v148 offset:8448
	ds_read_b128 v[60:63], v148 offset:8512
	ds_read_b128 v[64:67], v148 offset:8576
	ds_read_b128 v[68:71], v148 offset:8640
	s_waitcnt lgkmcnt(0)
	v_mfma_f32_16x16x32_bf16 v[56:59], v[32:35], v[56:59], 0
	v_mfma_f32_16x16x32_bf16 v[56:59], v[36:39], v[60:63], v[56:59]
	v_mfma_f32_16x16x32_bf16 v[56:59], v[40:43], v[64:67], v[56:59]
	v_mfma_f32_16x16x32_bf16 v[56:59], v[44:47], v[68:71], v[56:59]
	v_fma_f32 v60, -v125, v133, v241
	v_fma_f32 v61, v125, v132, v245
	v_fmac_f32_e32 v60, v122, v132
	v_fmac_f32_e32 v61, v122, v133
	v_fma_f32 v63, -v125, v61, v240
	v_fmac_f32_e32 v244, v125, v60
	v_fmac_f32_e32 v63, v122, v60
	v_fmac_f32_e32 v244, v122, v61
	v_cvt_pk_bf16_f32 v62, v60, v61
	v_cvt_pk_bf16_f32 v60, v63, v244
	ds_write2_b32 v162, v60, v62 offset0:120 offset1:188
	v_fma_f32 v60, -v125, v244, v239
	v_fma_f32 v61, v125, v63, v243
	v_fmac_f32_e32 v60, v122, v63
	v_fmac_f32_e32 v61, v122, v244
	v_fma_f32 v63, -v125, v61, v238
	v_fmac_f32_e32 v242, v125, v60
	v_fmac_f32_e32 v63, v122, v60
	v_fmac_f32_e32 v242, v122, v61
	v_cvt_pk_bf16_f32 v62, v60, v61
	v_cvt_pk_bf16_f32 v60, v63, v242
	ds_write2_b32 v163, v60, v62 offset0:112 offset1:180
	v_fma_f32 v60, -v125, v242, v233
	v_fma_f32 v61, v125, v63, v237
	v_fmac_f32_e32 v60, v122, v63
	v_fmac_f32_e32 v61, v122, v242
	v_fma_f32 v63, -v125, v61, v232
	v_fmac_f32_e32 v236, v125, v60
	v_fmac_f32_e32 v63, v122, v60
	v_fmac_f32_e32 v236, v122, v61
	v_cvt_pk_bf16_f32 v62, v60, v61
	v_cvt_pk_bf16_f32 v60, v63, v236
	ds_write2_b32 v164, v60, v62 offset0:104 offset1:172
	v_fma_f32 v60, -v125, v236, v231
	v_fma_f32 v61, v125, v63, v235
	v_fmac_f32_e32 v60, v122, v63
	v_fmac_f32_e32 v61, v122, v236
	v_fma_f32 v63, -v125, v61, v230
	v_fmac_f32_e32 v234, v125, v60
	v_fmac_f32_e32 v63, v122, v60
	v_fmac_f32_e32 v234, v122, v61
	v_cvt_pk_bf16_f32 v62, v60, v61
	v_cvt_pk_bf16_f32 v60, v63, v234
	ds_write2_b32 v165, v60, v62 offset0:96 offset1:164
	v_fma_f32 v60, -v125, v234, v225
	v_fma_f32 v61, v125, v63, v229
	v_fmac_f32_e32 v60, v122, v63
	v_fmac_f32_e32 v61, v122, v234
	v_fma_f32 v63, -v125, v61, v224
	v_fmac_f32_e32 v228, v125, v60
	v_fmac_f32_e32 v63, v122, v60
	v_fmac_f32_e32 v228, v122, v61
	v_cvt_pk_bf16_f32 v62, v60, v61
	v_cvt_pk_bf16_f32 v60, v63, v228
	ds_write2_b32 v166, v60, v62 offset0:88 offset1:156
	v_fma_f32 v60, -v125, v228, v223
	v_fma_f32 v61, v125, v63, v227
	v_fmac_f32_e32 v60, v122, v63
	v_fmac_f32_e32 v61, v122, v228
	v_fma_f32 v63, -v125, v61, v222
	v_fmac_f32_e32 v226, v125, v60
	v_fmac_f32_e32 v63, v122, v60
	v_fmac_f32_e32 v226, v122, v61
	v_cvt_pk_bf16_f32 v62, v60, v61
	v_cvt_pk_bf16_f32 v60, v63, v226
	ds_write2_b32 v167, v60, v62 offset0:80 offset1:148
	v_fma_f32 v60, -v125, v226, v217
	v_fma_f32 v61, v125, v63, v221
	v_fmac_f32_e32 v60, v122, v63
	v_fmac_f32_e32 v61, v122, v226
	v_fma_f32 v63, -v125, v61, v216
	v_fmac_f32_e32 v220, v125, v60
	v_fmac_f32_e32 v63, v122, v60
	v_fmac_f32_e32 v220, v122, v61
	v_cvt_pk_bf16_f32 v62, v60, v61
	v_cvt_pk_bf16_f32 v60, v63, v220
	ds_write2_b32 v168, v60, v62 offset0:72 offset1:140
	v_fma_f32 v60, -v125, v220, v215
	v_fma_f32 v61, v125, v63, v219
	v_fmac_f32_e32 v60, v122, v63
	v_fmac_f32_e32 v61, v122, v220
	v_fma_f32 v63, -v125, v61, v214
	v_fmac_f32_e32 v218, v125, v60
	v_fmac_f32_e32 v63, v122, v60
	v_fmac_f32_e32 v218, v122, v61
	v_cvt_pk_bf16_f32 v62, v60, v61
	v_cvt_pk_bf16_f32 v60, v63, v218
	ds_write2_b32 v169, v60, v62 offset0:64 offset1:132
	v_mov_b32_e32 v132, v63
	v_mov_b32_e32 v133, v218
	v_mfma_f32_16x16x32_bf16 v[214:217], v[48:51], v[178:181], 0
	v_mfma_f32_16x16x32_bf16 v[222:225], v[48:51], v[186:189], 0
	v_mfma_f32_16x16x32_bf16 v[230:233], v[48:51], v[194:197], 0
	v_mfma_f32_16x16x32_bf16 v[238:241], v[48:51], v[202:205], 0
	v_mfma_f32_16x16x32_bf16 v[218:221], v[48:51], v[182:185], 0
	v_mfma_f32_16x16x32_bf16 v[226:229], v[48:51], v[190:193], 0
	v_mfma_f32_16x16x32_bf16 v[234:237], v[48:51], v[198:201], 0
	v_mfma_f32_16x16x32_bf16 v[242:245], v[48:51], v[206:209], 0
	v_cvt_pk_bf16_f32 v56, v56, v57
	v_cvt_pk_bf16_f32 v57, v58, v59
	v_lshl_add_u64 v[62:63], s[0:1], 0, v[104:105]
	v_lshlrev_b64 v[62:63], 11, v[62:63]
	v_lshl_add_u64 v[62:63], v[128:129], 0, v[62:63]
	global_store_dwordx2 v[62:63], v[56:57], off nt
	v_permlane32_swap_b32_e32 v214, v230
	v_permlane32_swap_b32_e32 v222, v238
	v_permlane32_swap_b32_e32 v215, v231
	v_permlane32_swap_b32_e32 v223, v239
	v_permlane32_swap_b32_e32 v216, v232
	v_permlane32_swap_b32_e32 v224, v240
	v_permlane32_swap_b32_e32 v217, v233
	v_permlane32_swap_b32_e32 v225, v241
	v_permlane16_swap_b32_e32 v214, v222
	v_permlane16_swap_b32_e32 v230, v238
	v_permlane16_swap_b32_e32 v215, v223
	v_permlane16_swap_b32_e32 v231, v239
	v_permlane16_swap_b32_e32 v216, v224
	v_permlane16_swap_b32_e32 v232, v240
	v_permlane16_swap_b32_e32 v217, v225
	v_permlane16_swap_b32_e32 v233, v241
	v_permlane32_swap_b32_e32 v218, v234
	v_permlane32_swap_b32_e32 v226, v242
	v_permlane32_swap_b32_e32 v219, v235
	v_permlane32_swap_b32_e32 v227, v243
	v_permlane32_swap_b32_e32 v220, v236
	v_permlane32_swap_b32_e32 v228, v244
	v_permlane32_swap_b32_e32 v221, v237
	v_permlane32_swap_b32_e32 v229, v245
	v_permlane16_swap_b32_e32 v218, v226
	v_permlane16_swap_b32_e32 v234, v242
	v_permlane16_swap_b32_e32 v219, v227
	v_permlane16_swap_b32_e32 v235, v243
	v_permlane16_swap_b32_e32 v220, v228
	v_permlane16_swap_b32_e32 v236, v244
	v_permlane16_swap_b32_e32 v221, v229
	v_permlane16_swap_b32_e32 v237, v245
	s_mov_b64 s[0:1], s[26:27]
	v_mov_b32_e32 v48, v173
	v_mov_b32_e32 v49, v172
	v_mov_b32_e32 v50, v171
	v_mov_b32_e32 v51, v170
	s_add_i32 s25, s25, 1
	s_cmp_eq_u32 s25, 17
	s_cbranch_scc1 .Ls5f_bwd_entry
; #define LAS __attribute__((address_space(3)))
; DI unsigned pk2(float lo, float hi) { f32x2 v = {lo, hi}; bf16x2_t b = __builtin_convertvector(v, bf16x2_t); return __builtin_bit_cast(unsigned, b); }
; #define LDS_WAIT() asm volatile("s_waitcnt lgkmcnt(0)" ::: "memory")
; #define MFMA16(a, b, c) __builtin_amdgcn_mfma_f32_16x16x32_bf16((a), (b), (c), 0, 0, 0)
; DI void s5_phase(const KArgs& a, int zz, int o, const bf16_t* H, bf16_t* YF, bf16_t* YB, LAS unsigned char* lds, int G, int bid, int wave, int lane) {
;     ...
;         for (int ci = 1; ci < 272; ++ci) iter(ci, true);
;         {
;             f32x4 ya = (f32x4){0.f, 0.f, 0.f, 0.f};
; #pragma unroll
;             for (int kb = 0; kb < 4; ++kb) { const bf16x8 Ax = *(const LAS bf16x8*)(XS + fr * 68 + kb * 16 + fq * 4); ya = MFMA16(Cb[kb], Ax, ya); }
;             u32x2 w; w.x = pk2(ya[0], ya[1]); w.y = pk2(ya[2], ya[3]); *(u32x2*)(Y + (rowprev + fr) * D + g * 16 + fq * 4) = w;
;         }
;         LDS_WAIT();
	s_cmpk_lg_i32 s25, 0x110
	s_cbranch_scc1 .LBB0_414
	s_waitcnt vmcnt(0)
	ds_read_b128 v[48:51], v148 offset:8448
	ds_read_b128 v[52:55], v148 offset:8512
	s_mov_b32 s36, s12
	s_waitcnt lgkmcnt(1)
	v_mfma_f32_16x16x32_bf16 v[48:51], v[32:35], v[48:51], 0
	s_waitcnt lgkmcnt(0)
	v_mfma_f32_16x16x32_bf16 v[48:51], v[36:39], v[52:55], v[48:51]
	ds_read_b128 v[52:55], v148 offset:8576
	s_waitcnt lgkmcnt(0)
	v_mfma_f32_16x16x32_bf16 v[48:51], v[40:43], v[52:55], v[48:51]
	ds_read_b128 v[52:55], v148 offset:8640
	v_lshlrev_b32_e32 v148, 1, v106
	s_waitcnt lgkmcnt(0)
	v_mfma_f32_16x16x32_bf16 v[48:51], v[44:47], v[52:55], v[48:51]
	s_nop 7
	v_cvt_pk_bf16_f32 v48, v48, v49
	v_cvt_pk_bf16_f32 v49, v50, v51
	v_mov_b32_e32 v51, s27
	v_or_b32_e32 v50, s26, v104
	v_lshlrev_b64 v[50:51], 11, v[50:51]
	v_lshl_add_u64 v[50:51], s[6:7], 0, v[50:51]
	v_lshl_add_u64 v[50:51], s[52:53], 1, v[50:51]
	v_lshl_add_u64 v[50:51], v[50:51], 0, v[148:149]
	global_store_dwordx2 v[50:51], v[48:49], off
	s_waitcnt lgkmcnt(0)
	s_branch .LBB0_394

; #define LAS __attribute__((address_space(3)))
; DI unsigned pk2(float lo, float hi) { f32x2 v = {lo, hi}; bf16x2_t b = __builtin_convertvector(v, bf16x2_t); return __builtin_bit_cast(unsigned, b); }
; #define MFMA16(a, b, c) __builtin_amdgcn_mfma_f32_16x16x32_bf16((a), (b), (c), 0, 0, 0)
; #define S5_CB() asm volatile("" ::: "memory")
; DI void s5_phase(const KArgs& a, int zz, int o, const bf16_t* H, bf16_t* YF, bf16_t* YB, LAS unsigned char* lds, int G, int bid, int wave, int lane) {
;     ...
;         auto iter = [&](const int ci, const bool do_c) __attribute__((always_inline)) {
;             const size_t row0 = chunk_row(ci);
;             const u32x4 u3 = loadu(ci + 3);
;             f32x2 bu[16];
; #pragma unroll
;             for (int s = 0; s < 16; ++s) { const int tt = DIRC ? 15 - s : s; bu[s] = *(const LAS f32x2*)(BU + tt * 132 + 2 * lane); }
;             bf16x8 Ax[4];
;             if (do_c) {
; #pragma unroll
;                 for (int kb = 0; kb < 4; ++kb) Ax[kb] = *(const LAS bf16x8*)(XS + fr * 68 + kb * 16 + fq * 4); }
;             S5_CB();
;             stageA(u1);
;             S5_CB();
; #pragma unroll
;             for (int s = 0; s < 16; ++s) { const int tt = DIRC ? 15 - s : s;
;                 const float nr = __builtin_fmaf(abr, xr, __builtin_fmaf(nabi, xi, bu[s][0])); const float ni = __builtin_fmaf(abr, xi, __builtin_fmaf(abi, xr, bu[s][1])); xr = nr; xi = ni;
;                 XS[tt * 68 + lane] = pk2(xr, xi); }
;             if (do_c) {
;                 f32x4 ya = (f32x4){0.f, 0.f, 0.f, 0.f};
; #pragma unroll
;                 for (int kb = 0; kb < 4; ++kb) ya = MFMA16(Cb[kb], Ax[kb], ya);
;                 u32x2 w; w.x = pk2(ya[0], ya[1]); w.y = pk2(ya[2], ya[3]); *(u32x2*)(Y + (rowprev + fr) * D + g * 16 + fq * 4) = w; }
;             S5_CB();
;             rowprev = row0; u1 = u2; u2 = u3;
;         };
;         iter(0, false);
;         for (int ci = 1; ci < 272; ++ci) iter(ci, true);
.Ls5f_bwd_loop:
	ds_read_b128 v[56:59], v148 offset:8448
	ds_read_b128 v[60:63], v148 offset:8512
	ds_read_b128 v[64:67], v148 offset:8576
	ds_read_b128 v[68:71], v148 offset:8640
	s_waitcnt lgkmcnt(0)
	v_mfma_f32_16x16x32_bf16 v[56:59], v[32:35], v[56:59], 0
	v_mfma_f32_16x16x32_bf16 v[56:59], v[36:39], v[60:63], v[56:59]
	v_mfma_f32_16x16x32_bf16 v[56:59], v[40:43], v[64:67], v[56:59]
	v_mfma_f32_16x16x32_bf16 v[56:59], v[44:47], v[68:71], v[56:59]
	v_fma_f32 v60, -v125, v133, v241
	v_fma_f32 v61, v125, v132, v245
	v_fmac_f32_e32 v60, v122, v132
	v_fmac_f32_e32 v61, v122, v133
	v_fma_f32 v63, -v125, v61, v240
	v_fmac_f32_e32 v244, v125, v60
	v_fmac_f32_e32 v63, v122, v60
	v_fmac_f32_e32 v244, v122, v61
	v_cvt_pk_bf16_f32 v62, v60, v61
	v_cvt_pk_bf16_f32 v60, v63, v244
	ds_write2_b32 v162, v60, v62 offset0:120 offset1:188
	v_fma_f32 v60, -v125, v244, v239
	v_fma_f32 v61, v125, v63, v243
	v_fmac_f32_e32 v60, v122, v63
	v_fmac_f32_e32 v61, v122, v244
	v_fma_f32 v63, -v125, v61, v238
	v_fmac_f32_e32 v242, v125, v60
	v_fmac_f32_e32 v63, v122, v60
	v_fmac_f32_e32 v242, v122, v61
	v_cvt_pk_bf16_f32 v62, v60, v61
	v_cvt_pk_bf16_f32 v60, v63, v242
	ds_write2_b32 v163, v60, v62 offset0:112 offset1:180
	v_fma_f32 v60, -v125, v242, v233
	v_fma_f32 v61, v125, v63, v237
	v_fmac_f32_e32 v60, v122, v63
	v_fmac_f32_e32 v61, v122, v242
	v_fma_f32 v63, -v125, v61, v232
	v_fmac_f32_e32 v236, v125, v60
	v_fmac_f32_e32 v63, v122, v60
	v_fmac_f32_e32 v236, v122, v61
	v_cvt_pk_bf16_f32 v62, v60, v61
	v_cvt_pk_bf16_f32 v60, v63, v236
	ds_write2_b32 v164, v60, v62 offset0:104 offset1:172
	v_fma_f32 v60, -v125, v236, v231
	v_fma_f32 v61, v125, v63, v235
	v_fmac_f32_e32 v60, v122, v63
	v_fmac_f32_e32 v61, v122, v236
	v_fma_f32 v63, -v125, v61, v230
	v_fmac_f32_e32 v234, v125, v60
	v_fmac_f32_e32 v63, v122, v60
	v_fmac_f32_e32 v234, v122, v61
	v_cvt_pk_bf16_f32 v62, v60, v61
	v_cvt_pk_bf16_f32 v60, v63, v234
	ds_write2_b32 v165, v60, v62 offset0:96 offset1:164
	v_fma_f32 v60, -v125, v234, v225
	v_fma_f32 v61, v125, v63, v229
	v_fmac_f32_e32 v60, v122, v63
	v_fmac_f32_e32 v61, v122, v234
	v_fma_f32 v63, -v125, v61, v224
	v_fmac_f32_e32 v228, v125, v60
	v_fmac_f32_e32 v63, v122, v60
	v_fmac_f32_e32 v228, v122, v61
	v_cvt_pk_bf16_f32 v62, v60, v61
	v_cvt_pk_bf16_f32 v60, v63, v228
	ds_write2_b32 v166, v60, v62 offset0:88 offset1:156
	v_fma_f32 v60, -v125, v228, v223
	v_fma_f32 v61, v125, v63, v227
	v_fmac_f32_e32 v60, v122, v63
	v_fmac_f32_e32 v61, v122, v228
	v_fma_f32 v63, -v125, v61, v222
	v_fmac_f32_e32 v226, v125, v60
	v_fmac_f32_e32 v63, v122, v60
	v_fmac_f32_e32 v226, v122, v61
	v_cvt_pk_bf16_f32 v62, v60, v61
	v_cvt_pk_bf16_f32 v60, v63, v226
	ds_write2_b32 v167, v60, v62 offset0:80 offset1:148
	v_fma_f32 v60, -v125, v226, v217
	v_fma_f32 v61, v125, v63, v221
	v_fmac_f32_e32 v60, v122, v63
	v_fmac_f32_e32 v61, v122, v226
	v_fma_f32 v63, -v125, v61, v216
	v_fmac_f32_e32 v220, v125, v60
	v_fmac_f32_e32 v63, v122, v60
	v_fmac_f32_e32 v220, v122, v61
	v_cvt_pk_bf16_f32 v62, v60, v61
	v_cvt_pk_bf16_f32 v60, v63, v220
	ds_write2_b32 v168, v60, v62 offset0:72 offset1:140
	v_fma_f32 v60, -v125, v220, v215
	v_fma_f32 v61, v125, v63, v219
	v_fmac_f32_e32 v60, v122, v63
	v_fmac_f32_e32 v61, v122, v220
	v_fma_f32 v63, -v125, v61, v214
	v_fmac_f32_e32 v218, v125, v60
	v_fmac_f32_e32 v63, v122, v60
	v_fmac_f32_e32 v218, v122, v61
	v_cvt_pk_bf16_f32 v62, v60, v61
	v_cvt_pk_bf16_f32 v60, v63, v218
	ds_write2_b32 v169, v60, v62 offset0:64 offset1:132
	v_mov_b32_e32 v132, v63
	v_mov_b32_e32 v133, v218
	v_mfma_f32_16x16x32_bf16 v[214:217], v[48:51], v[178:181], 0
	v_mfma_f32_16x16x32_bf16 v[222:225], v[48:51], v[186:189], 0
	v_mfma_f32_16x16x32_bf16 v[230:233], v[48:51], v[194:197], 0
	v_mfma_f32_16x16x32_bf16 v[238:241], v[48:51], v[202:205], 0
	v_mfma_f32_16x16x32_bf16 v[218:221], v[48:51], v[182:185], 0
	v_mfma_f32_16x16x32_bf16 v[226:229], v[48:51], v[190:193], 0
	v_mfma_f32_16x16x32_bf16 v[234:237], v[48:51], v[198:201], 0
	v_mfma_f32_16x16x32_bf16 v[242:245], v[48:51], v[206:209], 0
	v_cvt_pk_bf16_f32 v56, v56, v57
	v_cvt_pk_bf16_f32 v57, v58, v59
	v_lshl_add_u64 v[62:63], s[98:99], 0, v[248:249]
	global_store_dwordx2 v[62:63], v[56:57], off nt
	v_permlane32_swap_b32_e32 v214, v230
	v_permlane32_swap_b32_e32 v222, v238
	v_permlane32_swap_b32_e32 v215, v231
	v_permlane32_swap_b32_e32 v223, v239
	v_permlane32_swap_b32_e32 v216, v232
	v_permlane32_swap_b32_e32 v224, v240
	v_permlane32_swap_b32_e32 v217, v233
	v_permlane32_swap_b32_e32 v225, v241
	v_permlane16_swap_b32_e32 v214, v222
	v_permlane16_swap_b32_e32 v230, v238
	v_permlane16_swap_b32_e32 v215, v223
	v_permlane16_swap_b32_e32 v231, v239
	v_permlane16_swap_b32_e32 v216, v224
	v_permlane16_swap_b32_e32 v232, v240
	v_permlane16_swap_b32_e32 v217, v225
	v_permlane16_swap_b32_e32 v233, v241
	v_permlane32_swap_b32_e32 v218, v234
	v_permlane32_swap_b32_e32 v226, v242
	v_permlane32_swap_b32_e32 v219, v235
	v_permlane32_swap_b32_e32 v227, v243
	v_permlane32_swap_b32_e32 v220, v236
	v_permlane32_swap_b32_e32 v228, v244
	v_permlane32_swap_b32_e32 v221, v237
	v_permlane32_swap_b32_e32 v229, v245
	v_permlane16_swap_b32_e32 v218, v226
	v_permlane16_swap_b32_e32 v234, v242
	v_permlane16_swap_b32_e32 v219, v227
	v_permlane16_swap_b32_e32 v235, v243
	v_permlane16_swap_b32_e32 v220, v228
	v_permlane16_swap_b32_e32 v236, v244
	v_permlane16_swap_b32_e32 v221, v229
	v_permlane16_swap_b32_e32 v237, v245
	s_waitcnt vmcnt(1)
	v_mov_b32_e32 v48, v52
	v_mov_b32_e32 v49, v53
	v_mov_b32_e32 v50, v54
	v_mov_b32_e32 v51, v55
	v_lshl_add_u64 v[62:63], s[98:99], 0, v[246:247]
	global_load_dwordx4 v[52:55], v[62:63], off
	s_sub_u32 s98, s98, 0x8000
	s_subb_u32 s99, s99, 0
	s_add_i32 s100, s100, 1
	s_cmp_lg_u32 s100, 0x10d
	s_cbranch_scc1 .Ls5f_bwd_loop
	s_waitcnt vmcnt(0)
	s_mov_b32 s25, 0x10d
	s_add_u32 s0, s58, 48
	s_addc_u32 s1, s59, 0
	s_branch .LBB0_414

; DI void s5_phase(const KArgs& a, int zz, int o, const bf16_t* H, bf16_t* YF, bf16_t* YB, LAS unsigned char* lds, int G, int bid, int wave, int lane) {
;     ...
;         auto loadu = [&](const int ci) __attribute__((always_inline)) -> u32x4 {
;             const int cc = ci < 272 ? ci : 271;
;             u32x4 r = *(const u32x4*)(Hg + (chunk_row(cc) + fr) * D);
;             const bool keep = fq < 2;
;             r.x = keep ? r.x : 0u; r.y = keep ? r.y : 0u; r.z = keep ? r.z : 0u; r.w = keep ? r.w : 0u;
;             return r; };
;         auto stageA = [&](const u32x4 uu) __attribute__((always_inline)) {
;             const bf16x8 Au = __builtin_bit_cast(bf16x8, uu);
; #pragma unroll
;             for (int nt = 0; nt < 8; ++nt) { const f32x4 acc = MFMA16(Bb[nt], Au, ((f32x4){0.f, 0.f, 0.f, 0.f}));
;                 *(LAS f32x4*)(BU + fr * 132 + 16 * nt + fq * 4) = acc; } };
;         u32x4 u1 = loadu(1), u2 = loadu(2);
;         stageA(loadu(0));
;         S5_CB();
;         size_t rowprev = 0;
;         auto iter = [&](const int ci, const bool do_c) __attribute__((always_inline)) {
;             const size_t row0 = chunk_row(ci);
;             const u32x4 u3 = loadu(ci + 3);
;             f32x2 bu[16];
; #pragma unroll
;             for (int s = 0; s < 16; ++s) { const int tt = DIRC ? 15 - s : s; bu[s] = *(const LAS f32x2*)(BU + tt * 132 + 2 * lane); }
;             bf16x8 Ax[4];
;             if (do_c) {
; #pragma unroll
;                 for (int kb = 0; kb < 4; ++kb) Ax[kb] = *(const LAS bf16x8*)(XS + fr * 68 + kb * 16 + fq * 4); }
;             S5_CB();
;             stageA(u1);
;             S5_CB();
; #pragma unroll
;             for (int s = 0; s < 16; ++s) { const int tt = DIRC ? 15 - s : s;
;                 const float nr = __builtin_fmaf(abr, xr, __builtin_fmaf(nabi, xi, bu[s][0])); const float ni = __builtin_fmaf(abr, xi, __builtin_fmaf(abi, xr, bu[s][1])); xr = nr; xi = ni;
;                 XS[tt * 68 + lane] = pk2(xr, xi); }
;             if (do_c) {
;                 f32x4 ya = (f32x4){0.f, 0.f, 0.f, 0.f};
; #pragma unroll
;                 for (int kb = 0; kb < 4; ++kb) ya = MFMA16(Cb[kb], Ax[kb], ya);
;                 u32x2 w; w.x = pk2(ya[0], ya[1]); w.y = pk2(ya[2], ya[3]); *(u32x2*)(Y + (rowprev + fr) * D + g * 16 + fq * 4) = w; }
;             S5_CB();
;             rowprev = row0; u1 = u2; u2 = u3;
;         };
;         iter(0, false);
.LBB0_417:
	s_waitcnt vmcnt(1)
	s_cmp_lt_u32 s23, 16
	s_cselect_b64 s[26:27], -1, 0
	s_add_i32 s25, s24, 0xfffeff00
	s_and_b64 s[26:27], s[26:27], exec
	s_cselect_b32 s25, s24, s25
	s_cselect_b32 s26, s54, s56
	s_cselect_b32 s27, s55, s57
	s_add_u32 s26, s26, s25
	s_addc_u32 s27, s27, 0
	s_min_i32 s25, s23, 0x10c
	s_cmp_lt_u32 s23, 13
	s_cselect_b64 s[30:31], -1, 0
	s_lshl_b32 s25, s25, 4
	s_and_b64 s[30:31], s[30:31], exec
	s_movk_i32 s30, 0xff30
	s_cselect_b32 s30, 0x10030, s30
	s_cselect_b32 s31, s55, s57
	s_cselect_b32 s34, s54, s56
	s_add_i32 s25, s25, s30
	s_add_u32 s25, s34, s25
	s_addc_u32 s30, s31, 0
	v_cndmask_b32_e64 v170, 0, v53, s[38:39]
	v_cndmask_b32_e64 v171, 0, v52, s[38:39]
	v_mov_b32_e32 v53, s30
	v_or_b32_e32 v52, s25, v104
	v_lshlrev_b64 v[52:53], 11, v[52:53]
	v_lshl_add_u64 v[52:53], v[126:127], 0, v[52:53]
	v_add_u32_e32 v132, v134, v107
	v_cndmask_b32_e64 v133, 0, v55, s[38:39]
	v_cndmask_b32_e64 v148, 0, v54, s[38:39]
	global_load_dwordx4 v[52:55], v[52:53], off
	ds_read_b128 v[56:59], v132 offset:8448
	ds_read_b128 v[60:63], v132 offset:8512
	ds_read_b128 v[64:67], v132 offset:8576
	ds_read_b128 v[68:71], v132 offset:8640
	s_waitcnt lgkmcnt(0)
	v_mfma_f32_16x16x32_bf16 v[56:59], v[32:35], v[56:59], 0
	v_mfma_f32_16x16x32_bf16 v[56:59], v[36:39], v[60:63], v[56:59]
	v_mfma_f32_16x16x32_bf16 v[56:59], v[40:43], v[64:67], v[56:59]
	v_mfma_f32_16x16x32_bf16 v[56:59], v[44:47], v[68:71], v[56:59]
	v_fma_f32 v60, -v125, v131, v214
	v_fma_f32 v61, v125, v130, v218
	v_fmac_f32_e32 v60, v122, v130
	v_fmac_f32_e32 v61, v122, v131
	v_fma_f32 v63, -v125, v61, v215
	v_fmac_f32_e32 v219, v125, v60
	v_fmac_f32_e32 v63, v122, v60
	v_fmac_f32_e32 v219, v122, v61
	v_cvt_pk_bf16_f32 v62, v60, v61
	v_cvt_pk_bf16_f32 v60, v63, v219
	ds_write2_b32 v169, v62, v60 offset0:64 offset1:132
	v_fma_f32 v60, -v125, v219, v216
	v_fma_f32 v61, v125, v63, v220
	v_fmac_f32_e32 v60, v122, v63
	v_fmac_f32_e32 v61, v122, v219
	v_fma_f32 v63, -v125, v61, v217
	v_fmac_f32_e32 v221, v125, v60
	v_fmac_f32_e32 v63, v122, v60
	v_fmac_f32_e32 v221, v122, v61
	v_cvt_pk_bf16_f32 v62, v60, v61
	v_cvt_pk_bf16_f32 v60, v63, v221
	ds_write2_b32 v168, v62, v60 offset0:72 offset1:140
	v_fma_f32 v60, -v125, v221, v222
	v_fma_f32 v61, v125, v63, v226
	v_fmac_f32_e32 v60, v122, v63
	v_fmac_f32_e32 v61, v122, v221
	v_fma_f32 v63, -v125, v61, v223
	v_fmac_f32_e32 v227, v125, v60
	v_fmac_f32_e32 v63, v122, v60
	v_fmac_f32_e32 v227, v122, v61
	v_cvt_pk_bf16_f32 v62, v60, v61
	v_cvt_pk_bf16_f32 v60, v63, v227
	ds_write2_b32 v167, v62, v60 offset0:80 offset1:148
	v_fma_f32 v60, -v125, v227, v224
	v_fma_f32 v61, v125, v63, v228
	v_fmac_f32_e32 v60, v122, v63
	v_fmac_f32_e32 v61, v122, v227
	v_fma_f32 v63, -v125, v61, v225
	v_fmac_f32_e32 v229, v125, v60
	v_fmac_f32_e32 v63, v122, v60
	v_fmac_f32_e32 v229, v122, v61
	v_cvt_pk_bf16_f32 v62, v60, v61
	v_cvt_pk_bf16_f32 v60, v63, v229
	ds_write2_b32 v166, v62, v60 offset0:88 offset1:156
	v_fma_f32 v60, -v125, v229, v230
	v_fma_f32 v61, v125, v63, v234
	v_fmac_f32_e32 v60, v122, v63
	v_fmac_f32_e32 v61, v122, v229
	v_fma_f32 v63, -v125, v61, v231
	v_fmac_f32_e32 v235, v125, v60
	v_fmac_f32_e32 v63, v122, v60
	v_fmac_f32_e32 v235, v122, v61
	v_cvt_pk_bf16_f32 v62, v60, v61
	v_cvt_pk_bf16_f32 v60, v63, v235
	ds_write2_b32 v165, v62, v60 offset0:96 offset1:164
	v_fma_f32 v60, -v125, v235, v232
	v_fma_f32 v61, v125, v63, v236
	v_fmac_f32_e32 v60, v122, v63
	v_fmac_f32_e32 v61, v122, v235
	v_fma_f32 v63, -v125, v61, v233
	v_fmac_f32_e32 v237, v125, v60
	v_fmac_f32_e32 v63, v122, v60
	v_fmac_f32_e32 v237, v122, v61
	v_cvt_pk_bf16_f32 v62, v60, v61
	v_cvt_pk_bf16_f32 v60, v63, v237
	ds_write2_b32 v164, v62, v60 offset0:104 offset1:172
	v_fma_f32 v60, -v125, v237, v238
	v_fma_f32 v61, v125, v63, v242
	v_fmac_f32_e32 v60, v122, v63
	v_fmac_f32_e32 v61, v122, v237
	v_fma_f32 v63, -v125, v61, v239
	v_fmac_f32_e32 v243, v125, v60
	v_fmac_f32_e32 v63, v122, v60
	v_fmac_f32_e32 v243, v122, v61
	v_cvt_pk_bf16_f32 v62, v60, v61
	v_cvt_pk_bf16_f32 v60, v63, v243
	ds_write2_b32 v163, v62, v60 offset0:112 offset1:180
	v_fma_f32 v60, -v125, v243, v240
	v_fma_f32 v61, v125, v63, v244
	v_fmac_f32_e32 v60, v122, v63
	v_fmac_f32_e32 v61, v122, v243
	v_fma_f32 v63, -v125, v61, v241
	v_fmac_f32_e32 v245, v125, v60
	v_fmac_f32_e32 v63, v122, v60
	v_fmac_f32_e32 v245, v122, v61
	v_cvt_pk_bf16_f32 v62, v60, v61
	v_cvt_pk_bf16_f32 v60, v63, v245
	ds_write2_b32 v162, v62, v60 offset0:120 offset1:188
	v_mov_b32_e32 v130, v63
	v_mov_b32_e32 v131, v245
	v_mfma_f32_16x16x32_bf16 v[214:217], v[48:51], v[178:181], 0
	v_mfma_f32_16x16x32_bf16 v[222:225], v[48:51], v[186:189], 0
	v_mfma_f32_16x16x32_bf16 v[230:233], v[48:51], v[194:197], 0
	v_mfma_f32_16x16x32_bf16 v[238:241], v[48:51], v[202:205], 0
	v_mfma_f32_16x16x32_bf16 v[218:221], v[48:51], v[182:185], 0
	v_mfma_f32_16x16x32_bf16 v[226:229], v[48:51], v[190:193], 0
	v_mfma_f32_16x16x32_bf16 v[234:237], v[48:51], v[198:201], 0
	v_mfma_f32_16x16x32_bf16 v[242:245], v[48:51], v[206:209], 0
	v_cvt_pk_bf16_f32 v56, v56, v57
	v_cvt_pk_bf16_f32 v57, v58, v59
	v_lshl_add_u64 v[62:63], s[0:1], 0, v[104:105]
	v_lshlrev_b64 v[62:63], 11, v[62:63]
	v_lshl_add_u64 v[62:63], v[128:129], 0, v[62:63]
	global_store_dwordx2 v[62:63], v[56:57], off nt
	v_permlane32_swap_b32_e32 v214, v230
	v_permlane32_swap_b32_e32 v222, v238
	v_permlane32_swap_b32_e32 v215, v231
	v_permlane32_swap_b32_e32 v223, v239
	v_permlane32_swap_b32_e32 v216, v232
	v_permlane32_swap_b32_e32 v224, v240
	v_permlane32_swap_b32_e32 v217, v233
	v_permlane32_swap_b32_e32 v225, v241
	v_permlane16_swap_b32_e32 v214, v222
	v_permlane16_swap_b32_e32 v230, v238
	v_permlane16_swap_b32_e32 v215, v223
	v_permlane16_swap_b32_e32 v231, v239
	v_permlane16_swap_b32_e32 v216, v224
	v_permlane16_swap_b32_e32 v232, v240
	v_permlane16_swap_b32_e32 v217, v225
	v_permlane16_swap_b32_e32 v233, v241
	v_permlane32_swap_b32_e32 v218, v234
	v_permlane32_swap_b32_e32 v226, v242
	v_permlane32_swap_b32_e32 v219, v235
	v_permlane32_swap_b32_e32 v227, v243
	v_permlane32_swap_b32_e32 v220, v236
	v_permlane32_swap_b32_e32 v228, v244
	v_permlane32_swap_b32_e32 v221, v237
	v_permlane32_swap_b32_e32 v229, v245
	v_permlane16_swap_b32_e32 v218, v226
	v_permlane16_swap_b32_e32 v234, v242
	v_permlane16_swap_b32_e32 v219, v227
	v_permlane16_swap_b32_e32 v235, v243
	v_permlane16_swap_b32_e32 v220, v228
	v_permlane16_swap_b32_e32 v236, v244
	v_permlane16_swap_b32_e32 v221, v229
	v_permlane16_swap_b32_e32 v237, v245
	s_mov_b64 s[0:1], s[26:27]
	v_mov_b32_e32 v48, v171
	v_mov_b32_e32 v49, v170
	v_mov_b32_e32 v50, v148
	v_mov_b32_e32 v51, v133
	s_add_i32 s23, s23, 1
	s_add_i32 s24, s24, 16
	s_cmp_eq_u32 s23, 17
	s_cbranch_scc1 .Ls5f_fwd_entry
; #define LAS __attribute__((address_space(3)))
; DI unsigned pk2(float lo, float hi) { f32x2 v = {lo, hi}; bf16x2_t b = __builtin_convertvector(v, bf16x2_t); return __builtin_bit_cast(unsigned, b); }
; #define LDS_WAIT() asm volatile("s_waitcnt lgkmcnt(0)" ::: "memory")
; #define MFMA16(a, b, c) __builtin_amdgcn_mfma_f32_16x16x32_bf16((a), (b), (c), 0, 0, 0)
; DI void s5_phase(const KArgs& a, int zz, int o, const bf16_t* H, bf16_t* YF, bf16_t* YB, LAS unsigned char* lds, int G, int bid, int wave, int lane) {
;     ...
;         for (int ci = 1; ci < 272; ++ci) iter(ci, true);
;         {
;             f32x4 ya = (f32x4){0.f, 0.f, 0.f, 0.f};
; #pragma unroll
;             for (int kb = 0; kb < 4; ++kb) { const bf16x8 Ax = *(const LAS bf16x8*)(XS + fr * 68 + kb * 16 + fq * 4); ya = MFMA16(Cb[kb], Ax, ya); }
;             u32x2 w; w.x = pk2(ya[0], ya[1]); w.y = pk2(ya[2], ya[3]); *(u32x2*)(Y + (rowprev + fr) * D + g * 16 + fq * 4) = w;
;         }
;         LDS_WAIT();
	s_cmp_lg_u32 s24, 0x11100
	s_cbranch_scc1 .LBB0_417
	s_waitcnt vmcnt(0)
	ds_read_b128 v[0:3], v132 offset:8448
	ds_read_b128 v[4:7], v132 offset:8512
	v_lshlrev_b32_e32 v148, 1, v106
	s_waitcnt lgkmcnt(1)
	v_mfma_f32_16x16x32_bf16 v[0:3], v[32:35], v[0:3], 0
	s_waitcnt lgkmcnt(0)
	v_mfma_f32_16x16x32_bf16 v[0:3], v[36:39], v[4:7], v[0:3]
	ds_read_b128 v[4:7], v132 offset:8576
	s_waitcnt lgkmcnt(0)
	v_mfma_f32_16x16x32_bf16 v[0:3], v[40:43], v[4:7], v[0:3]
	ds_read_b128 v[4:7], v132 offset:8640
	s_waitcnt lgkmcnt(0)
	v_mfma_f32_16x16x32_bf16 v[0:3], v[44:47], v[4:7], v[0:3]
	s_nop 7
	v_cvt_pk_bf16_f32 v0, v0, v1
	v_cvt_pk_bf16_f32 v1, v2, v3
	v_mov_b32_e32 v3, s27
	v_or_b32_e32 v2, s26, v104
	v_lshlrev_b64 v[2:3], 11, v[2:3]
	v_lshl_add_u64 v[2:3], s[4:5], 0, v[2:3]
	v_lshl_add_u64 v[2:3], s[52:53], 1, v[2:3]
	v_lshl_add_u64 v[2:3], v[2:3], 0, v[148:149]
	global_store_dwordx2 v[2:3], v[0:1], off
	s_waitcnt lgkmcnt(0)
	s_branch .LBB0_394

; #define LAS __attribute__((address_space(3)))
; DI unsigned pk2(float lo, float hi) { f32x2 v = {lo, hi}; bf16x2_t b = __builtin_convertvector(v, bf16x2_t); return __builtin_bit_cast(unsigned, b); }
; #define MFMA16(a, b, c) __builtin_amdgcn_mfma_f32_16x16x32_bf16((a), (b), (c), 0, 0, 0)
; #define S5_CB() asm volatile("" ::: "memory")
; DI void s5_phase(const KArgs& a, int zz, int o, const bf16_t* H, bf16_t* YF, bf16_t* YB, LAS unsigned char* lds, int G, int bid, int wave, int lane) {
;     ...
;         auto iter = [&](const int ci, const bool do_c) __attribute__((always_inline)) {
;             const size_t row0 = chunk_row(ci);
;             const u32x4 u3 = loadu(ci + 3);
;             f32x2 bu[16];
; #pragma unroll
;             for (int s = 0; s < 16; ++s) { const int tt = DIRC ? 15 - s : s; bu[s] = *(const LAS f32x2*)(BU + tt * 132 + 2 * lane); }
;             bf16x8 Ax[4];
;             if (do_c) {
; #pragma unroll
;                 for (int kb = 0; kb < 4; ++kb) Ax[kb] = *(const LAS bf16x8*)(XS + fr * 68 + kb * 16 + fq * 4); }
;             S5_CB();
;             stageA(u1);
;             S5_CB();
; #pragma unroll
;             for (int s = 0; s < 16; ++s) { const int tt = DIRC ? 15 - s : s;
;                 const float nr = __builtin_fmaf(abr, xr, __builtin_fmaf(nabi, xi, bu[s][0])); const float ni = __builtin_fmaf(abr, xi, __builtin_fmaf(abi, xr, bu[s][1])); xr = nr; xi = ni;
;                 XS[tt * 68 + lane] = pk2(xr, xi); }
;             if (do_c) {
;                 f32x4 ya = (f32x4){0.f, 0.f, 0.f, 0.f};
; #pragma unroll
;                 for (int kb = 0; kb < 4; ++kb) ya = MFMA16(Cb[kb], Ax[kb], ya);
;                 u32x2 w; w.x = pk2(ya[0], ya[1]); w.y = pk2(ya[2], ya[3]); *(u32x2*)(Y + (rowprev + fr) * D + g * 16 + fq * 4) = w; }
;             S5_CB();
;             rowprev = row0; u1 = u2; u2 = u3;
;         };
;         iter(0, false);
;         for (int ci = 1; ci < 272; ++ci) iter(ci, true);
.Ls5f_fwd_loop:
	ds_read_b128 v[56:59], v132 offset:8448
	ds_read_b128 v[60:63], v132 offset:8512
	ds_read_b128 v[64:67], v132 offset:8576
	ds_read_b128 v[68:71], v132 offset:8640
	s_waitcnt lgkmcnt(0)
	v_mfma_f32_16x16x32_bf16 v[56:59], v[32:35], v[56:59], 0
	v_mfma_f32_16x16x32_bf16 v[56:59], v[36:39], v[60:63], v[56:59]
	v_mfma_f32_16x16x32_bf16 v[56:59], v[40:43], v[64:67], v[56:59]
	v_mfma_f32_16x16x32_bf16 v[56:59], v[44:47], v[68:71], v[56:59]
	v_fma_f32 v60, -v125, v131, v214
	v_fma_f32 v61, v125, v130, v218
	v_fmac_f32_e32 v60, v122, v130
	v_fmac_f32_e32 v61, v122, v131
	v_fma_f32 v63, -v125, v61, v215
	v_fmac_f32_e32 v219, v125, v60
	v_fmac_f32_e32 v63, v122, v60
	v_fmac_f32_e32 v219, v122, v61
	v_cvt_pk_bf16_f32 v62, v60, v61
	v_cvt_pk_bf16_f32 v60, v63, v219
	ds_write2_b32 v169, v62, v60 offset0:64 offset1:132
	v_fma_f32 v60, -v125, v219, v216
	v_fma_f32 v61, v125, v63, v220
	v_fmac_f32_e32 v60, v122, v63
	v_fmac_f32_e32 v61, v122, v219
	v_fma_f32 v63, -v125, v61, v217
	v_fmac_f32_e32 v221, v125, v60
	v_fmac_f32_e32 v63, v122, v60
	v_fmac_f32_e32 v221, v122, v61
	v_cvt_pk_bf16_f32 v62, v60, v61
	v_cvt_pk_bf16_f32 v60, v63, v221
	ds_write2_b32 v168, v62, v60 offset0:72 offset1:140
	v_fma_f32 v60, -v125, v221, v222
	v_fma_f32 v61, v125, v63, v226
	v_fmac_f32_e32 v60, v122, v63
	v_fmac_f32_e32 v61, v122, v221
	v_fma_f32 v63, -v125, v61, v223
	v_fmac_f32_e32 v227, v125, v60
	v_fmac_f32_e32 v63, v122, v60
	v_fmac_f32_e32 v227, v122, v61
	v_cvt_pk_bf16_f32 v62, v60, v61
	v_cvt_pk_bf16_f32 v60, v63, v227
	ds_write2_b32 v167, v62, v60 offset0:80 offset1:148
	v_fma_f32 v60, -v125, v227, v224
	v_fma_f32 v61, v125, v63, v228
	v_fmac_f32_e32 v60, v122, v63
	v_fmac_f32_e32 v61, v122, v227
	v_fma_f32 v63, -v125, v61, v225
	v_fmac_f32_e32 v229, v125, v60
	v_fmac_f32_e32 v63, v122, v60
	v_fmac_f32_e32 v229, v122, v61
	v_cvt_pk_bf16_f32 v62, v60, v61
	v_cvt_pk_bf16_f32 v60, v63, v229
	ds_write2_b32 v166, v62, v60 offset0:88 offset1:156
	v_fma_f32 v60, -v125, v229, v230
	v_fma_f32 v61, v125, v63, v234
	v_fmac_f32_e32 v60, v122, v63
	v_fmac_f32_e32 v61, v122, v229
	v_fma_f32 v63, -v125, v61, v231
	v_fmac_f32_e32 v235, v125, v60
	v_fmac_f32_e32 v63, v122, v60
	v_fmac_f32_e32 v235, v122, v61
	v_cvt_pk_bf16_f32 v62, v60, v61
	v_cvt_pk_bf16_f32 v60, v63, v235
	ds_write2_b32 v165, v62, v60 offset0:96 offset1:164
	v_fma_f32 v60, -v125, v235, v232
	v_fma_f32 v61, v125, v63, v236
	v_fmac_f32_e32 v60, v122, v63
	v_fmac_f32_e32 v61, v122, v235
	v_fma_f32 v63, -v125, v61, v233
	v_fmac_f32_e32 v237, v125, v60
	v_fmac_f32_e32 v63, v122, v60
	v_fmac_f32_e32 v237, v122, v61
	v_cvt_pk_bf16_f32 v62, v60, v61
	v_cvt_pk_bf16_f32 v60, v63, v237
	ds_write2_b32 v164, v62, v60 offset0:104 offset1:172
	v_fma_f32 v60, -v125, v237, v238
	v_fma_f32 v61, v125, v63, v242
	v_fmac_f32_e32 v60, v122, v63
	v_fmac_f32_e32 v61, v122, v237
	v_fma_f32 v63, -v125, v61, v239
	v_fmac_f32_e32 v243, v125, v60
	v_fmac_f32_e32 v63, v122, v60
	v_fmac_f32_e32 v243, v122, v61
	v_cvt_pk_bf16_f32 v62, v60, v61
	v_cvt_pk_bf16_f32 v60, v63, v243
	ds_write2_b32 v163, v62, v60 offset0:112 offset1:180
	v_fma_f32 v60, -v125, v243, v240
	v_fma_f32 v61, v125, v63, v244
	v_fmac_f32_e32 v60, v122, v63
	v_fmac_f32_e32 v61, v122, v243
	v_fma_f32 v63, -v125, v61, v241
	v_fmac_f32_e32 v245, v125, v60
	v_fmac_f32_e32 v63, v122, v60
	v_fmac_f32_e32 v245, v122, v61
	v_cvt_pk_bf16_f32 v62, v60, v61
	v_cvt_pk_bf16_f32 v60, v63, v245
	ds_write2_b32 v162, v62, v60 offset0:120 offset1:188
	v_mov_b32_e32 v130, v63
	v_mov_b32_e32 v131, v245
	v_mfma_f32_16x16x32_bf16 v[214:217], v[48:51], v[178:181], 0
	v_mfma_f32_16x16x32_bf16 v[222:225], v[48:51], v[186:189], 0
	v_mfma_f32_16x16x32_bf16 v[230:233], v[48:51], v[194:197], 0
	v_mfma_f32_16x16x32_bf16 v[238:241], v[48:51], v[202:205], 0
	v_mfma_f32_16x16x32_bf16 v[218:221], v[48:51], v[182:185], 0
	v_mfma_f32_16x16x32_bf16 v[226:229], v[48:51], v[190:193], 0
	v_mfma_f32_16x16x32_bf16 v[234:237], v[48:51], v[198:201], 0
	v_mfma_f32_16x16x32_bf16 v[242:245], v[48:51], v[206:209], 0
	v_cvt_pk_bf16_f32 v56, v56, v57
	v_cvt_pk_bf16_f32 v57, v58, v59
	v_lshl_add_u64 v[62:63], s[98:99], 0, v[248:249]
	global_store_dwordx2 v[62:63], v[56:57], off nt
	v_permlane32_swap_b32_e32 v214, v230
	v_permlane32_swap_b32_e32 v222, v238
	v_permlane32_swap_b32_e32 v215, v231
	v_permlane32_swap_b32_e32 v223, v239
	v_permlane32_swap_b32_e32 v216, v232
	v_permlane32_swap_b32_e32 v224, v240
	v_permlane32_swap_b32_e32 v217, v233
	v_permlane32_swap_b32_e32 v225, v241
	v_permlane16_swap_b32_e32 v214, v222
	v_permlane16_swap_b32_e32 v230, v238
	v_permlane16_swap_b32_e32 v215, v223
	v_permlane16_swap_b32_e32 v231, v239
	v_permlane16_swap_b32_e32 v216, v224
	v_permlane16_swap_b32_e32 v232, v240
	v_permlane16_swap_b32_e32 v217, v225
	v_permlane16_swap_b32_e32 v233, v241
	v_permlane32_swap_b32_e32 v218, v234
	v_permlane32_swap_b32_e32 v226, v242
	v_permlane32_swap_b32_e32 v219, v235
	v_permlane32_swap_b32_e32 v227, v243
	v_permlane32_swap_b32_e32 v220, v236
	v_permlane32_swap_b32_e32 v228, v244
	v_permlane32_swap_b32_e32 v221, v237
	v_permlane32_swap_b32_e32 v229, v245
	v_permlane16_swap_b32_e32 v218, v226
	v_permlane16_swap_b32_e32 v234, v242
	v_permlane16_swap_b32_e32 v219, v227
	v_permlane16_swap_b32_e32 v235, v243
	v_permlane16_swap_b32_e32 v220, v228
	v_permlane16_swap_b32_e32 v236, v244
	v_permlane16_swap_b32_e32 v221, v229
	v_permlane16_swap_b32_e32 v237, v245
	s_waitcnt vmcnt(1)
	v_mov_b32_e32 v48, v52
	v_mov_b32_e32 v49, v53
	v_mov_b32_e32 v50, v54
	v_mov_b32_e32 v51, v55
	v_lshl_add_u64 v[62:63], s[98:99], 0, v[246:247]
	global_load_dwordx4 v[52:55], v[62:63], off
	s_add_u32 s98, s98, 0x8000
	s_addc_u32 s99, s99, 0
	s_add_i32 s100, s100, 1
	s_cmp_lg_u32 s100, 0x10d
	s_cbranch_scc1 .Ls5f_fwd_loop
	s_waitcnt vmcnt(0)
	s_mov_b32 s23, 0x10d
	s_mov_b32 s24, 0x110d0
	s_add_u32 s0, s56, 0xfc0
	s_addc_u32 s1, s57, 0
	s_branch .LBB0_417
